# plus: attention epilogues stage the 32x128 tile through LDS and store 8x16 B per lane instead of 64x2 B (row addresses via an LDS table), all three modes
# baseline (speedup 1.0000x reference)
.LBB0_200:
	s_or_b64 exec, exec, s[12:13]
	s_waitcnt lgkmcnt(0)
	ds_read_b128 v[68:71], v172
	v_add_lshl_u32 v74, s61, v173, 6
	v_or_b32_e32 v72, v190, v74
	s_mov_b32 s91, s57
	v_ashrrev_i32_e32 v73, 31, v72
	s_mov_b32 s93, s57
	v_lshl_add_u64 v[72:73], v[72:73], 0, s[90:91]
	s_waitcnt lgkmcnt(0)
	v_mul_f32_e32 v50, v50, v68
	v_lshl_add_u64 v[66:67], v[116:117], 0, s[92:93]
	v_lshlrev_b64 v[72:73], 12, v[72:73]
	v_bfe_u32 v75, v50, 16, 1
	v_lshl_add_u64 v[72:73], v[66:67], 0, v[72:73]
	v_add3_u32 v50, v50, v75, s71
	v_mul_f32_e32 v34, v34, v68
	v_readlane_b32 s32, v255, 9
	v_mbcnt_lo_u32_b32 v84, -1, 0
	v_mbcnt_hi_u32_b32 v84, -1, v84
	v_mov_b32_e32 v85, s32
	v_lshrrev_b32_e32 v86, 1, v85
	v_lshlrev_b32_e32 v86, 15, v86
	v_and_b32_e32 v87, 1, v85
	v_lshl_add_u32 v86, v87, 13, v86
	v_add_u32_e32 v86, 0x4000, v86
	v_lshlrev_b32_e32 v87, 9, v85
	v_add_u32_e32 v87, 0x20500, v87
	v_lshrrev_b32_e32 v88, 5, v84
	v_and_b32_e32 v89, 31, v84
	v_lshlrev_b32_e32 v90, 10, v88
	v_lshl_add_u32 v90, v89, 1, v90
	v_add_u32_e32 v90, v86, v90
	v_lshl_add_u32 v91, v88, 5, v87
	v_and_b32_e32 v92, -64, v72
	v_mov_b32_e32 v93, v73
	ds_write_b64 v91, v[92:93] offset:0
	ds_write_b16_d16_hi v90, v50 offset:0
	v_bfe_u32 v50, v34, 16, 1
	v_add3_u32 v34, v34, v50, s71
	v_mul_f32_e32 v18, v18, v68
	ds_write_b16_d16_hi v90, v34 offset:64
	v_bfe_u32 v34, v18, 16, 1
	v_add3_u32 v18, v18, v34, s71
	v_mul_f32_e32 v2, v2, v68
	ds_write_b16_d16_hi v90, v18 offset:128
	v_bfe_u32 v18, v2, 16, 1
	v_add3_u32 v2, v2, v18, s71
	ds_write_b16_d16_hi v90, v2 offset:192
	v_or_b32_e32 v72, v191, v74
	v_ashrrev_i32_e32 v73, 31, v72
	v_lshl_add_u64 v[72:73], v[72:73], 0, s[90:91]
	v_mul_f32_e32 v2, v51, v69
	v_lshlrev_b64 v[72:73], 12, v[72:73]
	v_bfe_u32 v18, v2, 16, 1
	v_lshl_add_u64 v[72:73], v[66:67], 0, v[72:73]
	v_add3_u32 v2, v2, v18, s71
	v_and_b32_e32 v92, -64, v72
	v_mov_b32_e32 v93, v73
	ds_write_b64 v91, v[92:93] offset:8
	ds_write_b16_d16_hi v90, v2 offset:256
	v_mul_f32_e32 v2, v35, v69
	v_bfe_u32 v18, v2, 16, 1
	v_add3_u32 v2, v2, v18, s71
	ds_write_b16_d16_hi v90, v2 offset:320
	v_mul_f32_e32 v2, v19, v69
	v_bfe_u32 v18, v2, 16, 1
	v_add3_u32 v2, v2, v18, s71
	ds_write_b16_d16_hi v90, v2 offset:384
	v_mul_f32_e32 v2, v3, v69
	v_bfe_u32 v3, v2, 16, 1
	v_add3_u32 v2, v2, v3, s71
	ds_write_b16_d16_hi v90, v2 offset:448
	v_or_b32_e32 v2, v192, v74
	v_ashrrev_i32_e32 v3, 31, v2
	v_lshl_add_u64 v[2:3], v[2:3], 0, s[90:91]
	v_mul_f32_e32 v18, v52, v70
	v_lshlrev_b64 v[2:3], 12, v[2:3]
	v_bfe_u32 v19, v18, 16, 1
	v_lshl_add_u64 v[2:3], v[66:67], 0, v[2:3]
	v_add3_u32 v18, v18, v19, s71
	v_and_b32_e32 v92, -64, v2
	v_mov_b32_e32 v93, v3
	ds_write_b64 v91, v[92:93] offset:16
	ds_write_b16_d16_hi v90, v18 offset:512
	v_mul_f32_e32 v18, v36, v70
	v_bfe_u32 v19, v18, 16, 1
	v_add3_u32 v18, v18, v19, s71
	ds_write_b16_d16_hi v90, v18 offset:576
	v_mul_f32_e32 v18, v20, v70
	v_bfe_u32 v19, v18, 16, 1
	v_add3_u32 v18, v18, v19, s71
	v_mul_f32_e32 v4, v4, v70
	ds_write_b16_d16_hi v90, v18 offset:640
	v_bfe_u32 v18, v4, 16, 1
	v_add3_u32 v4, v4, v18, s71
	ds_write_b16_d16_hi v90, v4 offset:704
	v_or_b32_e32 v2, v193, v74
	v_ashrrev_i32_e32 v3, 31, v2
	v_lshl_add_u64 v[2:3], v[2:3], 0, s[90:91]
	v_mul_f32_e32 v4, v53, v71
	v_lshlrev_b64 v[2:3], 12, v[2:3]
	v_bfe_u32 v18, v4, 16, 1
	v_lshl_add_u64 v[2:3], v[66:67], 0, v[2:3]
	v_add3_u32 v4, v4, v18, s71
	v_and_b32_e32 v92, -64, v2
	v_mov_b32_e32 v93, v3
	ds_write_b64 v91, v[92:93] offset:24
	ds_write_b16_d16_hi v90, v4 offset:768
	v_mul_f32_e32 v4, v37, v71
	v_bfe_u32 v18, v4, 16, 1
	v_add3_u32 v4, v4, v18, s71
	ds_write_b16_d16_hi v90, v4 offset:832
	v_mul_f32_e32 v4, v21, v71
	v_bfe_u32 v18, v4, 16, 1
	v_add3_u32 v4, v4, v18, s71
	ds_write_b16_d16_hi v90, v4 offset:896
	v_mul_f32_e32 v4, v5, v71
	v_bfe_u32 v5, v4, 16, 1
	v_add3_u32 v4, v4, v5, s71
	ds_write_b16_d16_hi v90, v4 offset:960
	ds_read_b128 v[2:5], v172 offset:32
	v_add_u32_e32 v18, s61, v174
	v_lshl_or_b32 v18, v18, 6, v194
	v_ashrrev_i32_e32 v19, 31, v18
	v_lshl_add_u64 v[18:19], v[18:19], 0, s[90:91]
	s_waitcnt lgkmcnt(0)
	v_mul_f32_e32 v20, v54, v2
	v_lshlrev_b64 v[18:19], 12, v[18:19]
	v_bfe_u32 v21, v20, 16, 1
	v_lshl_add_u64 v[18:19], v[66:67], 0, v[18:19]
	v_add3_u32 v20, v20, v21, s71
	v_and_b32_e32 v92, -64, v18
	v_mov_b32_e32 v93, v19
	ds_write_b64 v91, v[92:93] offset:64
	ds_write_b16_d16_hi v90, v20 offset:2048
	v_mul_f32_e32 v20, v38, v2
	v_bfe_u32 v21, v20, 16, 1
	v_add3_u32 v20, v20, v21, s71
	ds_write_b16_d16_hi v90, v20 offset:2112
	v_mul_f32_e32 v20, v22, v2
	v_mul_f32_e32 v2, v6, v2
	v_bfe_u32 v6, v2, 16, 1
	v_bfe_u32 v21, v20, 16, 1
	v_add3_u32 v2, v2, v6, s71
	v_add3_u32 v20, v20, v21, s71
	ds_write_b16_d16_hi v90, v2 offset:2240
	v_add_u32_e32 v2, s61, v175
	ds_write_b16_d16_hi v90, v20 offset:2176
	v_lshl_or_b32 v18, v2, 6, v195
	v_ashrrev_i32_e32 v19, 31, v18
	v_lshl_add_u64 v[18:19], v[18:19], 0, s[90:91]
	v_mul_f32_e32 v2, v55, v3
	v_lshlrev_b64 v[18:19], 12, v[18:19]
	v_bfe_u32 v6, v2, 16, 1
	v_lshl_add_u64 v[18:19], v[66:67], 0, v[18:19]
	v_add3_u32 v2, v2, v6, s71
	v_and_b32_e32 v92, -64, v18
	v_mov_b32_e32 v93, v19
	ds_write_b64 v91, v[92:93] offset:72
	ds_write_b16_d16_hi v90, v2 offset:2304
	v_mul_f32_e32 v2, v39, v3
	v_bfe_u32 v6, v2, 16, 1
	v_add3_u32 v2, v2, v6, s71
	ds_write_b16_d16_hi v90, v2 offset:2368
	v_mul_f32_e32 v2, v23, v3
	v_bfe_u32 v6, v2, 16, 1
	v_add3_u32 v2, v2, v6, s71
	ds_write_b16_d16_hi v90, v2 offset:2432
	v_mul_f32_e32 v2, v7, v3
	v_bfe_u32 v3, v2, 16, 1
	v_add3_u32 v2, v2, v3, s71
	ds_write_b16_d16_hi v90, v2 offset:2496
	v_add_u32_e32 v2, s61, v176
	v_lshl_or_b32 v2, v2, 6, v196
	v_ashrrev_i32_e32 v3, 31, v2
	v_lshl_add_u64 v[2:3], v[2:3], 0, s[90:91]
	v_mul_f32_e32 v6, v56, v4
	v_lshlrev_b64 v[2:3], 12, v[2:3]
	v_bfe_u32 v7, v6, 16, 1
	v_lshl_add_u64 v[2:3], v[66:67], 0, v[2:3]
	v_add3_u32 v6, v6, v7, s71
	v_and_b32_e32 v92, -64, v2
	v_mov_b32_e32 v93, v3
	ds_write_b64 v91, v[92:93] offset:80
	ds_write_b16_d16_hi v90, v6 offset:2560
	v_mul_f32_e32 v6, v40, v4
	v_bfe_u32 v7, v6, 16, 1
	v_add3_u32 v6, v6, v7, s71
	ds_write_b16_d16_hi v90, v6 offset:2624
	v_mul_f32_e32 v6, v24, v4
	v_bfe_u32 v7, v6, 16, 1
	v_add3_u32 v6, v6, v7, s71
	v_mul_f32_e32 v4, v8, v4
	ds_write_b16_d16_hi v90, v6 offset:2688
	v_bfe_u32 v6, v4, 16, 1
	v_add3_u32 v4, v4, v6, s71
	ds_write_b16_d16_hi v90, v4 offset:2752
	v_add_u32_e32 v2, s61, v177
	v_lshl_or_b32 v2, v2, 6, v197
	v_ashrrev_i32_e32 v3, 31, v2
	v_lshl_add_u64 v[2:3], v[2:3], 0, s[90:91]
	v_mul_f32_e32 v4, v57, v5
	v_lshlrev_b64 v[2:3], 12, v[2:3]
	v_bfe_u32 v6, v4, 16, 1
	v_lshl_add_u64 v[2:3], v[66:67], 0, v[2:3]
	v_add3_u32 v4, v4, v6, s71
	v_and_b32_e32 v92, -64, v2
	v_mov_b32_e32 v93, v3
	ds_write_b64 v91, v[92:93] offset:88
	ds_write_b16_d16_hi v90, v4 offset:2816
	v_mul_f32_e32 v4, v41, v5
	v_bfe_u32 v6, v4, 16, 1
	v_add3_u32 v4, v4, v6, s71
	ds_write_b16_d16_hi v90, v4 offset:2880
	v_mul_f32_e32 v4, v25, v5
	v_bfe_u32 v6, v4, 16, 1
	v_add3_u32 v4, v4, v6, s71
	ds_write_b16_d16_hi v90, v4 offset:2944
	v_mul_f32_e32 v4, v9, v5
	v_bfe_u32 v5, v4, 16, 1
	v_add3_u32 v4, v4, v5, s71
	ds_write_b16_d16_hi v90, v4 offset:3008
	ds_read_b128 v[2:5], v172 offset:64
	v_add_u32_e32 v6, s61, v178
	v_lshl_or_b32 v6, v6, 6, v190
	v_ashrrev_i32_e32 v7, 31, v6
	v_lshl_add_u64 v[6:7], v[6:7], 0, s[90:91]
	s_waitcnt lgkmcnt(0)
	v_mul_f32_e32 v8, v58, v2
	v_lshlrev_b64 v[6:7], 12, v[6:7]
	v_bfe_u32 v9, v8, 16, 1
	v_lshl_add_u64 v[6:7], v[66:67], 0, v[6:7]
	v_add3_u32 v8, v8, v9, s71
	v_and_b32_e32 v92, -64, v6
	v_mov_b32_e32 v93, v7
	ds_write_b64 v91, v[92:93] offset:128
	ds_write_b16_d16_hi v90, v8 offset:4096
	v_mul_f32_e32 v8, v42, v2
	v_bfe_u32 v9, v8, 16, 1
	v_add3_u32 v8, v8, v9, s71
	ds_write_b16_d16_hi v90, v8 offset:4160
	v_mul_f32_e32 v8, v26, v2
	v_bfe_u32 v9, v8, 16, 1
	v_add3_u32 v8, v8, v9, s71
	v_mul_f32_e32 v2, v10, v2
	ds_write_b16_d16_hi v90, v8 offset:4224
	v_bfe_u32 v8, v2, 16, 1
	v_add3_u32 v2, v2, v8, s71
	ds_write_b16_d16_hi v90, v2 offset:4288
	v_add_u32_e32 v2, s61, v179
	v_lshl_or_b32 v6, v2, 6, v198
	v_ashrrev_i32_e32 v7, 31, v6
	v_lshl_add_u64 v[6:7], v[6:7], 0, s[90:91]
	v_mul_f32_e32 v2, v59, v3
	v_lshlrev_b64 v[6:7], 12, v[6:7]
	v_bfe_u32 v8, v2, 16, 1
	v_lshl_add_u64 v[6:7], v[66:67], 0, v[6:7]
	v_add3_u32 v2, v2, v8, s71
	v_and_b32_e32 v92, -64, v6
	v_mov_b32_e32 v93, v7
	ds_write_b64 v91, v[92:93] offset:136
	ds_write_b16_d16_hi v90, v2 offset:4352
	v_mul_f32_e32 v2, v43, v3
	v_bfe_u32 v8, v2, 16, 1
	v_add3_u32 v2, v2, v8, s71
	ds_write_b16_d16_hi v90, v2 offset:4416
	v_mul_f32_e32 v2, v27, v3
	v_bfe_u32 v8, v2, 16, 1
	v_add3_u32 v2, v2, v8, s71
	ds_write_b16_d16_hi v90, v2 offset:4480
	v_mul_f32_e32 v2, v11, v3
	v_bfe_u32 v3, v2, 16, 1
	v_add3_u32 v2, v2, v3, s71
	ds_write_b16_d16_hi v90, v2 offset:4544
	v_add_u32_e32 v2, s61, v180
	v_lshl_or_b32 v2, v2, 6, v199
	v_ashrrev_i32_e32 v3, 31, v2
	v_lshl_add_u64 v[2:3], v[2:3], 0, s[90:91]
	v_mul_f32_e32 v6, v60, v4
	v_lshlrev_b64 v[2:3], 12, v[2:3]
	v_bfe_u32 v7, v6, 16, 1
	v_lshl_add_u64 v[2:3], v[66:67], 0, v[2:3]
	v_add3_u32 v6, v6, v7, s71
	v_and_b32_e32 v92, -64, v2
	v_mov_b32_e32 v93, v3
	ds_write_b64 v91, v[92:93] offset:144
	ds_write_b16_d16_hi v90, v6 offset:4608
	v_mul_f32_e32 v6, v44, v4
	v_bfe_u32 v7, v6, 16, 1
	v_add3_u32 v6, v6, v7, s71
	ds_write_b16_d16_hi v90, v6 offset:4672
	v_mul_f32_e32 v6, v28, v4
	v_bfe_u32 v7, v6, 16, 1
	v_add3_u32 v6, v6, v7, s71
	v_mul_f32_e32 v4, v12, v4
	ds_write_b16_d16_hi v90, v6 offset:4736
	v_bfe_u32 v6, v4, 16, 1
	v_add3_u32 v4, v4, v6, s71
	ds_write_b16_d16_hi v90, v4 offset:4800
	v_add_u32_e32 v2, s61, v181
	v_lshl_or_b32 v2, v2, 6, v204
	v_ashrrev_i32_e32 v3, 31, v2
	v_lshl_add_u64 v[2:3], v[2:3], 0, s[90:91]
	v_mul_f32_e32 v4, v61, v5
	v_lshlrev_b64 v[2:3], 12, v[2:3]
	v_bfe_u32 v6, v4, 16, 1
	v_lshl_add_u64 v[2:3], v[66:67], 0, v[2:3]
	v_add3_u32 v4, v4, v6, s71
	v_and_b32_e32 v92, -64, v2
	v_mov_b32_e32 v93, v3
	ds_write_b64 v91, v[92:93] offset:152
	ds_write_b16_d16_hi v90, v4 offset:4864
	v_mul_f32_e32 v4, v45, v5
	v_bfe_u32 v6, v4, 16, 1
	v_add3_u32 v4, v4, v6, s71
	ds_write_b16_d16_hi v90, v4 offset:4928
	v_mul_f32_e32 v4, v29, v5
	v_bfe_u32 v6, v4, 16, 1
	v_add3_u32 v4, v4, v6, s71
	ds_write_b16_d16_hi v90, v4 offset:4992
	v_mul_f32_e32 v4, v13, v5
	v_bfe_u32 v5, v4, 16, 1
	v_add3_u32 v4, v4, v5, s71
	ds_write_b16_d16_hi v90, v4 offset:5056
	ds_read_b128 v[2:5], v172 offset:96
	v_add_u32_e32 v6, s61, v182
	v_lshl_or_b32 v6, v6, 6, v205
	v_ashrrev_i32_e32 v7, 31, v6
	v_lshl_add_u64 v[6:7], v[6:7], 0, s[90:91]
	s_waitcnt lgkmcnt(0)
	v_mul_f32_e32 v8, v62, v2
	v_lshlrev_b64 v[6:7], 12, v[6:7]
	v_bfe_u32 v9, v8, 16, 1
	v_lshl_add_u64 v[6:7], v[66:67], 0, v[6:7]
	v_add3_u32 v8, v8, v9, s71
	v_and_b32_e32 v92, -64, v6
	v_mov_b32_e32 v93, v7
	ds_write_b64 v91, v[92:93] offset:192
	ds_write_b16_d16_hi v90, v8 offset:6144
	v_mul_f32_e32 v8, v46, v2
	v_bfe_u32 v9, v8, 16, 1
	v_add3_u32 v8, v8, v9, s71
	ds_write_b16_d16_hi v90, v8 offset:6208
	v_mul_f32_e32 v8, v30, v2
	v_bfe_u32 v9, v8, 16, 1
	v_add3_u32 v8, v8, v9, s71
	v_mul_f32_e32 v2, v14, v2
	ds_write_b16_d16_hi v90, v8 offset:6272
	v_bfe_u32 v8, v2, 16, 1
	v_add3_u32 v2, v2, v8, s71
	ds_write_b16_d16_hi v90, v2 offset:6336
	v_add_u32_e32 v2, s61, v183
	v_lshl_or_b32 v6, v2, 6, v206
	v_ashrrev_i32_e32 v7, 31, v6
	v_lshl_add_u64 v[6:7], v[6:7], 0, s[90:91]
	v_mul_f32_e32 v2, v63, v3
	v_lshlrev_b64 v[6:7], 12, v[6:7]
	v_bfe_u32 v8, v2, 16, 1
	v_lshl_add_u64 v[6:7], v[66:67], 0, v[6:7]
	v_add3_u32 v2, v2, v8, s71
	v_and_b32_e32 v92, -64, v6
	v_mov_b32_e32 v93, v7
	ds_write_b64 v91, v[92:93] offset:200
	ds_write_b16_d16_hi v90, v2 offset:6400
	v_mul_f32_e32 v2, v47, v3
	v_bfe_u32 v8, v2, 16, 1
	v_add3_u32 v2, v2, v8, s71
	ds_write_b16_d16_hi v90, v2 offset:6464
	v_mul_f32_e32 v2, v31, v3
	v_bfe_u32 v8, v2, 16, 1
	v_add3_u32 v2, v2, v8, s71
	ds_write_b16_d16_hi v90, v2 offset:6528
	v_mul_f32_e32 v2, v15, v3
	v_bfe_u32 v3, v2, 16, 1
	v_add3_u32 v2, v2, v3, s71
	ds_write_b16_d16_hi v90, v2 offset:6592
	v_add_u32_e32 v2, s61, v184
	v_lshl_or_b32 v2, v2, 6, v207
	v_ashrrev_i32_e32 v3, 31, v2
	v_lshl_add_u64 v[2:3], v[2:3], 0, s[90:91]
	v_mul_f32_e32 v6, v64, v4
	v_lshlrev_b64 v[2:3], 12, v[2:3]
	v_bfe_u32 v7, v6, 16, 1
	v_lshl_add_u64 v[2:3], v[66:67], 0, v[2:3]
	v_add3_u32 v6, v6, v7, s71
	v_and_b32_e32 v92, -64, v2
	v_mov_b32_e32 v93, v3
	ds_write_b64 v91, v[92:93] offset:208
	ds_write_b16_d16_hi v90, v6 offset:6656
	v_mul_f32_e32 v6, v48, v4
	v_bfe_u32 v7, v6, 16, 1
	v_add3_u32 v6, v6, v7, s71
	ds_write_b16_d16_hi v90, v6 offset:6720
	v_mul_f32_e32 v6, v32, v4
	v_bfe_u32 v7, v6, 16, 1
	v_add3_u32 v6, v6, v7, s71
	v_mul_f32_e32 v4, v16, v4
	ds_write_b16_d16_hi v90, v6 offset:6784
	v_bfe_u32 v6, v4, 16, 1
	v_add3_u32 v4, v4, v6, s71
	ds_write_b16_d16_hi v90, v4 offset:6848
	v_add_u32_e32 v2, s61, v185
	v_lshl_or_b32 v2, v2, 6, v208
	v_ashrrev_i32_e32 v3, 31, v2
	v_lshl_add_u64 v[2:3], v[2:3], 0, s[90:91]
	v_mul_f32_e32 v4, v65, v5
	v_lshlrev_b64 v[2:3], 12, v[2:3]
	v_bfe_u32 v6, v4, 16, 1
	v_lshl_add_u64 v[2:3], v[66:67], 0, v[2:3]
	v_add3_u32 v4, v4, v6, s71
	v_and_b32_e32 v92, -64, v2
	v_mov_b32_e32 v93, v3
	ds_write_b64 v91, v[92:93] offset:216
	ds_write_b16_d16_hi v90, v4 offset:6912
	v_mul_f32_e32 v4, v49, v5
	v_bfe_u32 v6, v4, 16, 1
	v_add3_u32 v4, v4, v6, s71
	ds_write_b16_d16_hi v90, v4 offset:6976
	v_mul_f32_e32 v4, v33, v5
	v_bfe_u32 v6, v4, 16, 1
	v_add3_u32 v4, v4, v6, s71
	ds_write_b16_d16_hi v90, v4 offset:7040
	v_mul_f32_e32 v4, v17, v5
	v_bfe_u32 v5, v4, 16, 1
	s_add_i32 s94, s94, s3
	s_add_i32 s55, s55, s78
	s_xor_b64 s[86:87], s[86:87], s[88:89]
	v_add3_u32 v4, v4, v5, s71
	s_cmpk_lt_i32 s94, 0x100
	ds_write_b16_d16_hi v90, v4 offset:7104
	v_lshrrev_b32_e32 v88, 4, v84
	v_and_b32_e32 v89, 15, v84
	v_lshlrev_b32_e32 v94, 8, v88
	v_lshl_add_u32 v94, v89, 4, v94
	v_add_u32_e32 v94, v86, v94
	v_lshl_add_u32 v95, v88, 3, v87
	v_lshlrev_b32_e32 v92, 4, v89
	v_mov_b32_e32 v93, 0
	ds_read_b128 v[2:5], v94
	ds_read_b128 v[6:9], v94 offset:1024
	ds_read_b128 v[10:13], v94 offset:2048
	ds_read_b128 v[14:17], v94 offset:3072
	ds_read_b128 v[18:21], v94 offset:4096
	ds_read_b128 v[22:25], v94 offset:5120
	ds_read_b128 v[26:29], v94 offset:6144
	ds_read_b128 v[30:33], v94 offset:7168
	ds_read_b64 v[34:35], v95
	ds_read_b64 v[36:37], v95 offset:32
	ds_read_b64 v[38:39], v95 offset:64
	ds_read_b64 v[40:41], v95 offset:96
	ds_read_b64 v[42:43], v95 offset:128
	ds_read_b64 v[44:45], v95 offset:160
	ds_read_b64 v[46:47], v95 offset:192
	ds_read_b64 v[48:49], v95 offset:224
	s_waitcnt lgkmcnt(0)
	v_lshl_add_u64 v[34:35], v[34:35], 0, v[92:93]
	global_store_dwordx4 v[34:35], v[2:5], off
	v_lshl_add_u64 v[36:37], v[36:37], 0, v[92:93]
	global_store_dwordx4 v[36:37], v[6:9], off
	v_lshl_add_u64 v[38:39], v[38:39], 0, v[92:93]
	global_store_dwordx4 v[38:39], v[10:13], off
	v_lshl_add_u64 v[40:41], v[40:41], 0, v[92:93]
	global_store_dwordx4 v[40:41], v[14:17], off
	v_lshl_add_u64 v[42:43], v[42:43], 0, v[92:93]
	global_store_dwordx4 v[42:43], v[18:21], off
	v_lshl_add_u64 v[44:45], v[44:45], 0, v[92:93]
	global_store_dwordx4 v[44:45], v[22:25], off
	v_lshl_add_u64 v[46:47], v[46:47], 0, v[92:93]
	global_store_dwordx4 v[46:47], v[26:29], off
	v_lshl_add_u64 v[48:49], v[48:49], 0, v[92:93]
	global_store_dwordx4 v[48:49], v[30:33], off
	s_cbranch_scc0 .LBB0_231

.LBB0_261:
	s_or_b64 exec, exec, s[20:21]
	v_add_u32_e32 v0, s0, v146
	ds_read_b128 v[68:71], v163
	v_lshlrev_b32_e32 v72, s31, v0
	v_lshlrev_b64 v[66:67], 24, v[66:67]
	v_add_u32_e32 v72, s34, v72
	v_lshl_add_u64 v[66:67], s[10:11], 0, v[66:67]
	s_lshl_b32 s56, s1, 1
	v_ashrrev_i32_e32 v73, 31, v72
	v_lshl_add_u64 v[66:67], v[66:67], 0, s[56:57]
	v_mov_b32_e32 v133, v1
	v_lshl_add_u64 v[72:73], s[18:19], 0, v[72:73]
	v_lshl_add_u64 v[66:67], v[66:67], 0, v[132:133]
	v_lshlrev_b64 v[72:73], 11, v[72:73]
	v_lshl_add_u64 v[72:73], v[66:67], 0, v[72:73]
	s_waitcnt lgkmcnt(0)
	v_fma_mixlo_f16 v2, v2, v68, 0
	v_readlane_b32 s32, v255, 9
	v_mbcnt_lo_u32_b32 v84, -1, 0
	v_mbcnt_hi_u32_b32 v84, -1, v84
	v_mov_b32_e32 v85, s32
	v_lshrrev_b32_e32 v86, 1, v85
	v_lshlrev_b32_e32 v86, 15, v86
	v_and_b32_e32 v87, 1, v85
	v_lshl_add_u32 v86, v87, 13, v86
	v_lshlrev_b32_e32 v87, 9, v85
	v_add_u32_e32 v87, 0x20500, v87
	v_lshrrev_b32_e32 v88, 5, v84
	v_and_b32_e32 v89, 31, v84
	v_lshlrev_b32_e32 v90, 10, v88
	v_lshl_add_u32 v90, v89, 1, v90
	v_add_u32_e32 v90, v86, v90
	v_lshl_add_u32 v91, v88, 5, v87
	v_and_b32_e32 v92, -64, v72
	v_mov_b32_e32 v93, v73
	ds_write_b64 v91, v[92:93] offset:0
	ds_write_b16 v90, v2 offset:192
	v_add_u32_e32 v2, s0, v165
	v_fma_mixlo_f16 v50, v50, v68, 0
	v_fma_mixlo_f16 v34, v34, v68, 0
	v_fma_mixlo_f16 v18, v18, v68, 0
	v_lshlrev_b32_e32 v2, s31, v2
	ds_write_b16 v90, v50 offset:0
	ds_write_b16 v90, v34 offset:64
	ds_write_b16 v90, v18 offset:128
	v_add_u32_e32 v72, s34, v2
	v_ashrrev_i32_e32 v73, 31, v72
	v_lshl_add_u64 v[72:73], s[18:19], 0, v[72:73]
	v_lshlrev_b64 v[72:73], 11, v[72:73]
	v_lshl_add_u64 v[72:73], v[66:67], 0, v[72:73]
	v_fma_mixlo_f16 v2, v51, v69, 0
	v_and_b32_e32 v92, -64, v72
	v_mov_b32_e32 v93, v73
	ds_write_b64 v91, v[92:93] offset:8
	ds_write_b16 v90, v2 offset:256
	v_fma_mixlo_f16 v2, v35, v69, 0
	ds_write_b16 v90, v2 offset:320
	v_fma_mixlo_f16 v2, v19, v69, 0
	ds_write_b16 v90, v2 offset:384
	v_fma_mixlo_f16 v2, v3, v69, 0
	ds_write_b16 v90, v2 offset:448
	v_add_u32_e32 v2, s0, v166
	v_lshlrev_b32_e32 v2, s31, v2
	v_add_u32_e32 v2, s34, v2
	v_ashrrev_i32_e32 v3, 31, v2
	v_lshl_add_u64 v[2:3], s[18:19], 0, v[2:3]
	v_lshlrev_b64 v[2:3], 11, v[2:3]
	v_lshl_add_u64 v[2:3], v[66:67], 0, v[2:3]
	v_fma_mixlo_f16 v18, v52, v70, 0
	v_and_b32_e32 v92, -64, v2
	v_mov_b32_e32 v93, v3
	ds_write_b64 v91, v[92:93] offset:16
	ds_write_b16 v90, v18 offset:512
	v_fma_mixlo_f16 v18, v36, v70, 0
	ds_write_b16 v90, v18 offset:576
	v_fma_mixlo_f16 v18, v20, v70, 0
	v_fma_mixlo_f16 v4, v4, v70, 0
	ds_write_b16 v90, v18 offset:640
	ds_write_b16 v90, v4 offset:704
	v_add_u32_e32 v2, s0, v167
	v_lshlrev_b32_e32 v2, s31, v2
	v_add_u32_e32 v2, s34, v2
	v_ashrrev_i32_e32 v3, 31, v2
	v_lshl_add_u64 v[2:3], s[18:19], 0, v[2:3]
	v_lshlrev_b64 v[2:3], 11, v[2:3]
	v_lshl_add_u64 v[2:3], v[66:67], 0, v[2:3]
	v_fma_mixlo_f16 v4, v53, v71, 0
	v_and_b32_e32 v92, -64, v2
	v_mov_b32_e32 v93, v3
	ds_write_b64 v91, v[92:93] offset:24
	ds_write_b16 v90, v4 offset:768
	v_fma_mixlo_f16 v4, v37, v71, 0
	ds_write_b16 v90, v4 offset:832
	v_fma_mixlo_f16 v4, v21, v71, 0
	ds_write_b16 v90, v4 offset:896
	v_fma_mixlo_f16 v4, v5, v71, 0
	ds_write_b16 v90, v4 offset:960
	ds_read_b128 v[2:5], v163 offset:32
	v_add_lshl_u32 v18, v0, 8, s31
	v_add_u32_e32 v18, s34, v18
	v_ashrrev_i32_e32 v19, 31, v18
	v_lshl_add_u64 v[18:19], s[18:19], 0, v[18:19]
	v_lshlrev_b64 v[18:19], 11, v[18:19]
	v_lshl_add_u64 v[18:19], v[66:67], 0, v[18:19]
	s_waitcnt lgkmcnt(0)
	v_fma_mixlo_f16 v20, v54, v2, 0
	v_and_b32_e32 v92, -64, v18
	v_mov_b32_e32 v93, v19
	ds_write_b64 v91, v[92:93] offset:64
	ds_write_b16 v90, v20 offset:2048
	v_fma_mixlo_f16 v20, v38, v2, 0
	ds_write_b16 v90, v20 offset:2112
	v_fma_mixlo_f16 v20, v22, v2, 0
	v_fma_mixlo_f16 v2, v6, v2, 0
	ds_write_b16 v90, v2 offset:2240
	v_add_lshl_u32 v2, v0, 9, s31
	ds_write_b16 v90, v20 offset:2176
	v_add_u32_e32 v18, s34, v2
	v_ashrrev_i32_e32 v19, 31, v18
	v_lshl_add_u64 v[18:19], s[18:19], 0, v[18:19]
	v_lshlrev_b64 v[18:19], 11, v[18:19]
	v_lshl_add_u64 v[18:19], v[66:67], 0, v[18:19]
	v_fma_mixlo_f16 v2, v55, v3, 0
	v_and_b32_e32 v92, -64, v18
	v_mov_b32_e32 v93, v19
	ds_write_b64 v91, v[92:93] offset:72
	ds_write_b16 v90, v2 offset:2304
	v_fma_mixlo_f16 v2, v39, v3, 0
	ds_write_b16 v90, v2 offset:2368
	v_fma_mixlo_f16 v2, v23, v3, 0
	ds_write_b16 v90, v2 offset:2432
	v_fma_mixlo_f16 v2, v7, v3, 0
	ds_write_b16 v90, v2 offset:2496
	v_add_lshl_u32 v2, v0, 10, s31
	v_add_u32_e32 v2, s34, v2
	v_ashrrev_i32_e32 v3, 31, v2
	v_lshl_add_u64 v[2:3], s[18:19], 0, v[2:3]
	v_lshlrev_b64 v[2:3], 11, v[2:3]
	v_lshl_add_u64 v[2:3], v[66:67], 0, v[2:3]
	v_fma_mixlo_f16 v6, v56, v4, 0
	v_and_b32_e32 v92, -64, v2
	v_mov_b32_e32 v93, v3
	ds_write_b64 v91, v[92:93] offset:80
	ds_write_b16 v90, v6 offset:2560
	v_fma_mixlo_f16 v6, v40, v4, 0
	ds_write_b16 v90, v6 offset:2624
	v_fma_mixlo_f16 v6, v24, v4, 0
	v_fma_mixlo_f16 v4, v8, v4, 0
	ds_write_b16 v90, v6 offset:2688
	ds_write_b16 v90, v4 offset:2752
	v_add_lshl_u32 v2, v0, 11, s31
	v_add_u32_e32 v2, s34, v2
	v_ashrrev_i32_e32 v3, 31, v2
	v_lshl_add_u64 v[2:3], s[18:19], 0, v[2:3]
	v_lshlrev_b64 v[2:3], 11, v[2:3]
	v_lshl_add_u64 v[2:3], v[66:67], 0, v[2:3]
	v_fma_mixlo_f16 v4, v57, v5, 0
	v_and_b32_e32 v92, -64, v2
	v_mov_b32_e32 v93, v3
	ds_write_b64 v91, v[92:93] offset:88
	ds_write_b16 v90, v4 offset:2816
	v_fma_mixlo_f16 v4, v41, v5, 0
	ds_write_b16 v90, v4 offset:2880
	v_fma_mixlo_f16 v4, v25, v5, 0
	ds_write_b16 v90, v4 offset:2944
	v_fma_mixlo_f16 v4, v9, v5, 0
	ds_write_b16 v90, v4 offset:3008
	ds_read_b128 v[2:5], v163 offset:64
	v_add_lshl_u32 v6, v0, 16, s31
	v_add_u32_e32 v6, s34, v6
	v_ashrrev_i32_e32 v7, 31, v6
	v_lshl_add_u64 v[6:7], s[18:19], 0, v[6:7]
	v_lshlrev_b64 v[6:7], 11, v[6:7]
	v_lshl_add_u64 v[6:7], v[66:67], 0, v[6:7]
	s_waitcnt lgkmcnt(0)
	v_fma_mixlo_f16 v8, v58, v2, 0
	v_and_b32_e32 v92, -64, v6
	v_mov_b32_e32 v93, v7
	ds_write_b64 v91, v[92:93] offset:128
	ds_write_b16 v90, v8 offset:4096
	v_fma_mixlo_f16 v8, v42, v2, 0
	ds_write_b16 v90, v8 offset:4160
	v_fma_mixlo_f16 v8, v26, v2, 0
	v_fma_mixlo_f16 v2, v10, v2, 0
	ds_write_b16 v90, v2 offset:4288
	v_add_lshl_u32 v2, v0, 17, s31
	ds_write_b16 v90, v8 offset:4224
	v_add_u32_e32 v6, s34, v2
	v_ashrrev_i32_e32 v7, 31, v6
	v_lshl_add_u64 v[6:7], s[18:19], 0, v[6:7]
	v_lshlrev_b64 v[6:7], 11, v[6:7]
	v_lshl_add_u64 v[6:7], v[66:67], 0, v[6:7]
	v_fma_mixlo_f16 v2, v59, v3, 0
	v_and_b32_e32 v92, -64, v6
	v_mov_b32_e32 v93, v7
	ds_write_b64 v91, v[92:93] offset:136
	ds_write_b16 v90, v2 offset:4352
	v_fma_mixlo_f16 v2, v43, v3, 0
	ds_write_b16 v90, v2 offset:4416
	v_fma_mixlo_f16 v2, v27, v3, 0
	ds_write_b16 v90, v2 offset:4480
	v_fma_mixlo_f16 v2, v11, v3, 0
	ds_write_b16 v90, v2 offset:4544
	v_add_lshl_u32 v2, v0, 18, s31
	v_add_u32_e32 v2, s34, v2
	v_ashrrev_i32_e32 v3, 31, v2
	v_lshl_add_u64 v[2:3], s[18:19], 0, v[2:3]
	v_lshlrev_b64 v[2:3], 11, v[2:3]
	v_lshl_add_u64 v[2:3], v[66:67], 0, v[2:3]
	v_fma_mixlo_f16 v6, v60, v4, 0
	v_and_b32_e32 v92, -64, v2
	v_mov_b32_e32 v93, v3
	ds_write_b64 v91, v[92:93] offset:144
	ds_write_b16 v90, v6 offset:4608
	v_fma_mixlo_f16 v6, v44, v4, 0
	ds_write_b16 v90, v6 offset:4672
	v_fma_mixlo_f16 v6, v28, v4, 0
	v_fma_mixlo_f16 v4, v12, v4, 0
	ds_write_b16 v90, v6 offset:4736
	ds_write_b16 v90, v4 offset:4800
	v_add_lshl_u32 v2, v0, 19, s31
	v_add_u32_e32 v2, s34, v2
	v_ashrrev_i32_e32 v3, 31, v2
	v_lshl_add_u64 v[2:3], s[18:19], 0, v[2:3]
	v_lshlrev_b64 v[2:3], 11, v[2:3]
	v_lshl_add_u64 v[2:3], v[66:67], 0, v[2:3]
	v_fma_mixlo_f16 v4, v61, v5, 0
	v_and_b32_e32 v92, -64, v2
	v_mov_b32_e32 v93, v3
	ds_write_b64 v91, v[92:93] offset:152
	ds_write_b16 v90, v4 offset:4864
	v_fma_mixlo_f16 v4, v45, v5, 0
	ds_write_b16 v90, v4 offset:4928
	v_fma_mixlo_f16 v4, v29, v5, 0
	ds_write_b16 v90, v4 offset:4992
	v_fma_mixlo_f16 v4, v13, v5, 0
	ds_write_b16 v90, v4 offset:5056
	ds_read_b128 v[2:5], v163 offset:96
	v_add_lshl_u32 v6, v0, 24, s31
	v_add_u32_e32 v6, s34, v6
	v_ashrrev_i32_e32 v7, 31, v6
	v_lshl_add_u64 v[6:7], s[18:19], 0, v[6:7]
	v_lshlrev_b64 v[6:7], 11, v[6:7]
	v_lshl_add_u64 v[6:7], v[66:67], 0, v[6:7]
	s_waitcnt lgkmcnt(0)
	v_fma_mixlo_f16 v8, v62, v2, 0
	v_and_b32_e32 v92, -64, v6
	v_mov_b32_e32 v93, v7
	ds_write_b64 v91, v[92:93] offset:192
	ds_write_b16 v90, v8 offset:6144
	v_fma_mixlo_f16 v8, v46, v2, 0
	ds_write_b16 v90, v8 offset:6208
	v_fma_mixlo_f16 v8, v30, v2, 0
	v_fma_mixlo_f16 v2, v14, v2, 0
	ds_write_b16 v90, v2 offset:6336
	v_add_lshl_u32 v2, v0, 25, s31
	ds_write_b16 v90, v8 offset:6272
	v_add_u32_e32 v6, s34, v2
	v_ashrrev_i32_e32 v7, 31, v6
	v_lshl_add_u64 v[6:7], s[18:19], 0, v[6:7]
	v_lshlrev_b64 v[6:7], 11, v[6:7]
	v_lshl_add_u64 v[6:7], v[66:67], 0, v[6:7]
	v_fma_mixlo_f16 v2, v63, v3, 0
	v_and_b32_e32 v92, -64, v6
	v_mov_b32_e32 v93, v7
	ds_write_b64 v91, v[92:93] offset:200
	ds_write_b16 v90, v2 offset:6400
	v_fma_mixlo_f16 v2, v47, v3, 0
	ds_write_b16 v90, v2 offset:6464
	v_fma_mixlo_f16 v2, v31, v3, 0
	ds_write_b16 v90, v2 offset:6528
	v_fma_mixlo_f16 v2, v15, v3, 0
	ds_write_b16 v90, v2 offset:6592
	v_add_lshl_u32 v2, v0, 26, s31
	v_add_u32_e32 v2, s34, v2
	v_ashrrev_i32_e32 v3, 31, v2
	v_lshl_add_u64 v[2:3], s[18:19], 0, v[2:3]
	v_lshlrev_b64 v[2:3], 11, v[2:3]
	v_lshl_add_u64 v[2:3], v[66:67], 0, v[2:3]
	v_fma_mixlo_f16 v6, v64, v4, 0
	v_and_b32_e32 v92, -64, v2
	v_mov_b32_e32 v93, v3
	ds_write_b64 v91, v[92:93] offset:208
	ds_write_b16 v90, v6 offset:6656
	v_fma_mixlo_f16 v6, v48, v4, 0
	ds_write_b16 v90, v6 offset:6720
	v_fma_mixlo_f16 v6, v32, v4, 0
	v_fma_mixlo_f16 v4, v16, v4, 0
	v_add_lshl_u32 v0, v0, 27, s31
	ds_write_b16 v90, v6 offset:6784
	ds_write_b16 v90, v4 offset:6848
	v_add_u32_e32 v2, s34, v0
	v_ashrrev_i32_e32 v3, 31, v2
	v_lshl_add_u64 v[2:3], s[18:19], 0, v[2:3]
	v_lshlrev_b64 v[2:3], 11, v[2:3]
	v_lshl_add_u64 v[2:3], v[66:67], 0, v[2:3]
	v_fma_mixlo_f16 v0, v65, v5, 0
	v_and_b32_e32 v92, -64, v2
	v_mov_b32_e32 v93, v3
	ds_write_b64 v91, v[92:93] offset:216
	ds_write_b16 v90, v0 offset:6912
	v_fma_mixlo_f16 v0, v49, v5, 0
	ds_write_b16 v90, v0 offset:6976
	v_fma_mixlo_f16 v0, v33, v5, 0
	s_add_i32 s24, s24, s23
	ds_write_b16 v90, v0 offset:7040
	v_fma_mixlo_f16 v0, v17, v5, 0
	s_cmpk_lt_i32 s24, 0x180
	ds_write_b16 v90, v0 offset:7104
	v_lshrrev_b32_e32 v88, 4, v84
	v_and_b32_e32 v89, 15, v84
	v_lshlrev_b32_e32 v94, 8, v88
	v_lshl_add_u32 v94, v89, 4, v94
	v_add_u32_e32 v94, v86, v94
	v_lshl_add_u32 v95, v88, 3, v87
	v_lshlrev_b32_e32 v92, 4, v89
	v_mov_b32_e32 v93, 0
	ds_read_b128 v[2:5], v94
	ds_read_b128 v[6:9], v94 offset:1024
	ds_read_b128 v[10:13], v94 offset:2048
	ds_read_b128 v[14:17], v94 offset:3072
	ds_read_b128 v[18:21], v94 offset:4096
	ds_read_b128 v[22:25], v94 offset:5120
	ds_read_b128 v[26:29], v94 offset:6144
	ds_read_b128 v[30:33], v94 offset:7168
	ds_read_b64 v[34:35], v95
	ds_read_b64 v[36:37], v95 offset:32
	ds_read_b64 v[38:39], v95 offset:64
	ds_read_b64 v[40:41], v95 offset:96
	ds_read_b64 v[42:43], v95 offset:128
	ds_read_b64 v[44:45], v95 offset:160
	ds_read_b64 v[46:47], v95 offset:192
	ds_read_b64 v[48:49], v95 offset:224
	s_waitcnt lgkmcnt(0)
	v_lshl_add_u64 v[34:35], v[34:35], 0, v[92:93]
	global_store_dwordx4 v[34:35], v[2:5], off
	v_lshl_add_u64 v[36:37], v[36:37], 0, v[92:93]
	global_store_dwordx4 v[36:37], v[6:9], off
	v_lshl_add_u64 v[38:39], v[38:39], 0, v[92:93]
	global_store_dwordx4 v[38:39], v[10:13], off
	v_lshl_add_u64 v[40:41], v[40:41], 0, v[92:93]
	global_store_dwordx4 v[40:41], v[14:17], off
	v_lshl_add_u64 v[42:43], v[42:43], 0, v[92:93]
	global_store_dwordx4 v[42:43], v[18:21], off
	v_lshl_add_u64 v[44:45], v[44:45], 0, v[92:93]
	global_store_dwordx4 v[44:45], v[22:25], off
	v_lshl_add_u64 v[46:47], v[46:47], 0, v[92:93]
	global_store_dwordx4 v[46:47], v[26:29], off
	v_lshl_add_u64 v[48:49], v[48:49], 0, v[92:93]
	global_store_dwordx4 v[48:49], v[30:33], off
	s_cbranch_scc0 .LBB0_283

.LBB0_310:
	s_or_b64 exec, exec, s[6:7]
	s_waitcnt lgkmcnt(0)
	ds_read_b128 v[2:5], v158
	v_add_u32_e32 v6, s0, v148
	v_ashrrev_i32_e32 v7, 31, v6
	v_lshl_add_u64 v[8:9], v[6:7], 0, s[56:57]
	v_lshlrev_b64 v[8:9], 12, v[8:9]
	v_lshl_add_u64 v[8:9], s[10:11], 0, v[8:9]
	s_lshl_b64 s[6:7], s[16:17], 1
	s_waitcnt vmcnt(0) lgkmcnt(0)
	v_mul_f32_e32 v0, v64, v2
	v_lshl_add_u64 v[8:9], v[8:9], 0, s[6:7]
	v_mov_b32_e32 v141, v1
	v_bfe_u32 v7, v0, 16, 1
	v_lshl_add_u64 v[8:9], v[8:9], 0, v[140:141]
	v_add3_u32 v0, v0, v7, s71
	v_readlane_b32 s32, v255, 9
	v_mbcnt_lo_u32_b32 v100, -1, 0
	v_mbcnt_hi_u32_b32 v100, -1, v100
	v_mov_b32_e32 v101, s32
	v_lshlrev_b32_e32 v102, 13, v101
	v_add_u32_e32 v102, 0x8000, v102
	v_lshlrev_b32_e32 v103, 9, v101
	v_add_u32_e32 v103, 0x20500, v103
	v_lshrrev_b32_e32 v104, 5, v100
	v_and_b32_e32 v105, 31, v100
	v_lshlrev_b32_e32 v106, 10, v104
	v_lshl_add_u32 v106, v105, 1, v106
	v_add_u32_e32 v106, v102, v106
	v_lshl_add_u32 v107, v104, 5, v103
	v_and_b32_e32 v108, -64, v8
	v_mov_b32_e32 v109, v9
	ds_write_b64 v107, v[108:109] offset:0
	ds_write_b16_d16_hi v106, v0 offset:0
	v_mul_f32_e32 v0, v48, v2
	v_bfe_u32 v7, v0, 16, 1
	v_add3_u32 v0, v0, v7, s71
	ds_write_b16_d16_hi v106, v0 offset:64
	v_mul_f32_e32 v0, v32, v2
	v_bfe_u32 v7, v0, 16, 1
	v_add3_u32 v0, v0, v7, s71
	ds_write_b16_d16_hi v106, v0 offset:128
	v_mul_f32_e32 v0, v16, v2
	v_bfe_u32 v2, v0, 16, 1
	v_add3_u32 v0, v0, v2, s71
	ds_write_b16_d16_hi v106, v0 offset:192
	v_add_u32_e32 v8, s0, v160
	v_ashrrev_i32_e32 v9, 31, v8
	v_lshl_add_u64 v[8:9], v[8:9], 0, s[56:57]
	v_lshlrev_b64 v[8:9], 12, v[8:9]
	v_lshl_add_u64 v[8:9], s[10:11], 0, v[8:9]
	v_mul_f32_e32 v0, v65, v3
	v_lshl_add_u64 v[8:9], v[8:9], 0, s[6:7]
	v_bfe_u32 v2, v0, 16, 1
	v_lshl_add_u64 v[8:9], v[8:9], 0, v[140:141]
	v_add3_u32 v0, v0, v2, s71
	v_and_b32_e32 v108, -64, v8
	v_mov_b32_e32 v109, v9
	ds_write_b64 v107, v[108:109] offset:8
	ds_write_b16_d16_hi v106, v0 offset:256
	v_mul_f32_e32 v0, v49, v3
	v_bfe_u32 v2, v0, 16, 1
	v_add3_u32 v0, v0, v2, s71
	ds_write_b16_d16_hi v106, v0 offset:320
	v_mul_f32_e32 v0, v33, v3
	v_bfe_u32 v2, v0, 16, 1
	v_add3_u32 v0, v0, v2, s71
	ds_write_b16_d16_hi v106, v0 offset:384
	v_mul_f32_e32 v0, v17, v3
	v_bfe_u32 v2, v0, 16, 1
	v_add3_u32 v0, v0, v2, s71
	v_add_u32_e32 v2, s0, v161
	v_ashrrev_i32_e32 v3, 31, v2
	v_lshl_add_u64 v[2:3], v[2:3], 0, s[56:57]
	v_lshlrev_b64 v[2:3], 12, v[2:3]
	ds_write_b16_d16_hi v106, v0 offset:448
	v_lshl_add_u64 v[2:3], s[10:11], 0, v[2:3]
	v_mul_f32_e32 v0, v66, v4
	v_lshl_add_u64 v[2:3], v[2:3], 0, s[6:7]
	v_bfe_u32 v7, v0, 16, 1
	v_lshl_add_u64 v[2:3], v[2:3], 0, v[140:141]
	v_add3_u32 v0, v0, v7, s71
	v_and_b32_e32 v108, -64, v2
	v_mov_b32_e32 v109, v3
	ds_write_b64 v107, v[108:109] offset:16
	ds_write_b16_d16_hi v106, v0 offset:512
	v_mul_f32_e32 v0, v50, v4
	v_bfe_u32 v7, v0, 16, 1
	v_add3_u32 v0, v0, v7, s71
	ds_write_b16_d16_hi v106, v0 offset:576
	v_mul_f32_e32 v0, v34, v4
	v_bfe_u32 v7, v0, 16, 1
	v_add3_u32 v0, v0, v7, s71
	ds_write_b16_d16_hi v106, v0 offset:640
	v_mul_f32_e32 v0, v18, v4
	v_bfe_u32 v4, v0, 16, 1
	v_add3_u32 v0, v0, v4, s71
	ds_write_b16_d16_hi v106, v0 offset:704
	v_add_u32_e32 v2, s0, v162
	v_ashrrev_i32_e32 v3, 31, v2
	v_lshl_add_u64 v[2:3], v[2:3], 0, s[56:57]
	v_lshlrev_b64 v[2:3], 12, v[2:3]
	v_lshl_add_u64 v[2:3], s[10:11], 0, v[2:3]
	v_mul_f32_e32 v0, v67, v5
	v_lshl_add_u64 v[2:3], v[2:3], 0, s[6:7]
	v_bfe_u32 v4, v0, 16, 1
	v_lshl_add_u64 v[2:3], v[2:3], 0, v[140:141]
	v_add3_u32 v0, v0, v4, s71
	v_and_b32_e32 v108, -64, v2
	v_mov_b32_e32 v109, v3
	ds_write_b64 v107, v[108:109] offset:24
	ds_write_b16_d16_hi v106, v0 offset:768
	v_mul_f32_e32 v0, v51, v5
	v_bfe_u32 v4, v0, 16, 1
	v_add3_u32 v0, v0, v4, s71
	ds_write_b16_d16_hi v106, v0 offset:832
	v_mul_f32_e32 v0, v35, v5
	v_bfe_u32 v4, v0, 16, 1
	v_add3_u32 v0, v0, v4, s71
	ds_write_b16_d16_hi v106, v0 offset:896
	v_mul_f32_e32 v0, v19, v5
	v_bfe_u32 v4, v0, 16, 1
	v_add3_u32 v0, v0, v4, s71
	ds_write_b16_d16_hi v106, v0 offset:960
	ds_read_b128 v[2:5], v158 offset:32
	v_add_u32_e32 v8, 8, v6
	v_ashrrev_i32_e32 v9, 31, v8
	v_lshl_add_u64 v[8:9], v[8:9], 0, s[56:57]
	v_lshlrev_b64 v[8:9], 12, v[8:9]
	v_lshl_add_u64 v[8:9], s[10:11], 0, v[8:9]
	s_waitcnt lgkmcnt(0)
	v_mul_f32_e32 v0, v68, v2
	v_lshl_add_u64 v[8:9], v[8:9], 0, s[6:7]
	v_bfe_u32 v7, v0, 16, 1
	v_lshl_add_u64 v[8:9], v[8:9], 0, v[140:141]
	v_add3_u32 v0, v0, v7, s71
	v_and_b32_e32 v108, -64, v8
	v_mov_b32_e32 v109, v9
	ds_write_b64 v107, v[108:109] offset:64
	ds_write_b16_d16_hi v106, v0 offset:2048
	v_mul_f32_e32 v0, v52, v2
	v_bfe_u32 v7, v0, 16, 1
	v_add3_u32 v0, v0, v7, s71
	ds_write_b16_d16_hi v106, v0 offset:2112
	v_mul_f32_e32 v0, v36, v2
	v_bfe_u32 v7, v0, 16, 1
	v_add3_u32 v0, v0, v7, s71
	ds_write_b16_d16_hi v106, v0 offset:2176
	v_mul_f32_e32 v0, v20, v2
	v_bfe_u32 v2, v0, 16, 1
	v_add3_u32 v0, v0, v2, s71
	ds_write_b16_d16_hi v106, v0 offset:2240
	v_add_u32_e32 v8, 9, v6
	v_ashrrev_i32_e32 v9, 31, v8
	v_lshl_add_u64 v[8:9], v[8:9], 0, s[56:57]
	v_lshlrev_b64 v[8:9], 12, v[8:9]
	v_lshl_add_u64 v[8:9], s[10:11], 0, v[8:9]
	v_mul_f32_e32 v0, v69, v3
	v_lshl_add_u64 v[8:9], v[8:9], 0, s[6:7]
	v_bfe_u32 v2, v0, 16, 1
	v_lshl_add_u64 v[8:9], v[8:9], 0, v[140:141]
	v_add3_u32 v0, v0, v2, s71
	v_and_b32_e32 v108, -64, v8
	v_mov_b32_e32 v109, v9
	ds_write_b64 v107, v[108:109] offset:72
	ds_write_b16_d16_hi v106, v0 offset:2304
	v_mul_f32_e32 v0, v53, v3
	v_bfe_u32 v2, v0, 16, 1
	v_add3_u32 v0, v0, v2, s71
	ds_write_b16_d16_hi v106, v0 offset:2368
	v_mul_f32_e32 v0, v37, v3
	v_bfe_u32 v2, v0, 16, 1
	v_add3_u32 v0, v0, v2, s71
	ds_write_b16_d16_hi v106, v0 offset:2432
	v_mul_f32_e32 v0, v21, v3
	v_bfe_u32 v2, v0, 16, 1
	v_add3_u32 v0, v0, v2, s71
	v_add_u32_e32 v2, 10, v6
	v_ashrrev_i32_e32 v3, 31, v2
	v_lshl_add_u64 v[2:3], v[2:3], 0, s[56:57]
	v_lshlrev_b64 v[2:3], 12, v[2:3]
	ds_write_b16_d16_hi v106, v0 offset:2496
	v_lshl_add_u64 v[2:3], s[10:11], 0, v[2:3]
	v_mul_f32_e32 v0, v70, v4
	v_lshl_add_u64 v[2:3], v[2:3], 0, s[6:7]
	v_bfe_u32 v7, v0, 16, 1
	v_lshl_add_u64 v[2:3], v[2:3], 0, v[140:141]
	v_add3_u32 v0, v0, v7, s71
	v_and_b32_e32 v108, -64, v2
	v_mov_b32_e32 v109, v3
	ds_write_b64 v107, v[108:109] offset:80
	ds_write_b16_d16_hi v106, v0 offset:2560
	v_mul_f32_e32 v0, v54, v4
	v_bfe_u32 v7, v0, 16, 1
	v_add3_u32 v0, v0, v7, s71
	ds_write_b16_d16_hi v106, v0 offset:2624
	v_mul_f32_e32 v0, v38, v4
	v_bfe_u32 v7, v0, 16, 1
	v_add3_u32 v0, v0, v7, s71
	ds_write_b16_d16_hi v106, v0 offset:2688
	v_mul_f32_e32 v0, v22, v4
	v_bfe_u32 v4, v0, 16, 1
	v_add3_u32 v0, v0, v4, s71
	ds_write_b16_d16_hi v106, v0 offset:2752
	v_add_u32_e32 v2, 11, v6
	v_ashrrev_i32_e32 v3, 31, v2
	v_lshl_add_u64 v[2:3], v[2:3], 0, s[56:57]
	v_lshlrev_b64 v[2:3], 12, v[2:3]
	v_lshl_add_u64 v[2:3], s[10:11], 0, v[2:3]
	v_mul_f32_e32 v0, v71, v5
	v_lshl_add_u64 v[2:3], v[2:3], 0, s[6:7]
	v_bfe_u32 v4, v0, 16, 1
	v_lshl_add_u64 v[2:3], v[2:3], 0, v[140:141]
	v_add3_u32 v0, v0, v4, s71
	v_and_b32_e32 v108, -64, v2
	v_mov_b32_e32 v109, v3
	ds_write_b64 v107, v[108:109] offset:88
	ds_write_b16_d16_hi v106, v0 offset:2816
	v_mul_f32_e32 v0, v55, v5
	v_bfe_u32 v4, v0, 16, 1
	v_add3_u32 v0, v0, v4, s71
	ds_write_b16_d16_hi v106, v0 offset:2880
	v_mul_f32_e32 v0, v39, v5
	v_bfe_u32 v4, v0, 16, 1
	v_add3_u32 v0, v0, v4, s71
	ds_write_b16_d16_hi v106, v0 offset:2944
	v_mul_f32_e32 v0, v23, v5
	v_bfe_u32 v4, v0, 16, 1
	v_add3_u32 v0, v0, v4, s71
	ds_write_b16_d16_hi v106, v0 offset:3008
	ds_read_b128 v[2:5], v158 offset:64
	v_add_u32_e32 v8, 16, v6
	v_ashrrev_i32_e32 v9, 31, v8
	v_lshl_add_u64 v[8:9], v[8:9], 0, s[56:57]
	v_lshlrev_b64 v[8:9], 12, v[8:9]
	v_lshl_add_u64 v[8:9], s[10:11], 0, v[8:9]
	s_waitcnt lgkmcnt(0)
	v_mul_f32_e32 v0, v72, v2
	v_lshl_add_u64 v[8:9], v[8:9], 0, s[6:7]
	v_bfe_u32 v7, v0, 16, 1
	v_lshl_add_u64 v[8:9], v[8:9], 0, v[140:141]
	v_add3_u32 v0, v0, v7, s71
	v_and_b32_e32 v108, -64, v8
	v_mov_b32_e32 v109, v9
	ds_write_b64 v107, v[108:109] offset:128
	ds_write_b16_d16_hi v106, v0 offset:4096
	v_mul_f32_e32 v0, v56, v2
	v_bfe_u32 v7, v0, 16, 1
	v_add3_u32 v0, v0, v7, s71
	ds_write_b16_d16_hi v106, v0 offset:4160
	v_mul_f32_e32 v0, v40, v2
	v_bfe_u32 v7, v0, 16, 1
	v_add3_u32 v0, v0, v7, s71
	ds_write_b16_d16_hi v106, v0 offset:4224
	v_mul_f32_e32 v0, v24, v2
	v_bfe_u32 v2, v0, 16, 1
	v_add3_u32 v0, v0, v2, s71
	ds_write_b16_d16_hi v106, v0 offset:4288
	v_add_u32_e32 v8, 17, v6
	v_ashrrev_i32_e32 v9, 31, v8
	v_lshl_add_u64 v[8:9], v[8:9], 0, s[56:57]
	v_lshlrev_b64 v[8:9], 12, v[8:9]
	v_lshl_add_u64 v[8:9], s[10:11], 0, v[8:9]
	v_mul_f32_e32 v0, v73, v3
	v_lshl_add_u64 v[8:9], v[8:9], 0, s[6:7]
	v_bfe_u32 v2, v0, 16, 1
	v_lshl_add_u64 v[8:9], v[8:9], 0, v[140:141]
	v_add3_u32 v0, v0, v2, s71
	v_and_b32_e32 v108, -64, v8
	v_mov_b32_e32 v109, v9
	ds_write_b64 v107, v[108:109] offset:136
	ds_write_b16_d16_hi v106, v0 offset:4352
	v_mul_f32_e32 v0, v57, v3
	v_bfe_u32 v2, v0, 16, 1
	v_add3_u32 v0, v0, v2, s71
	ds_write_b16_d16_hi v106, v0 offset:4416
	v_mul_f32_e32 v0, v41, v3
	v_bfe_u32 v2, v0, 16, 1
	v_add3_u32 v0, v0, v2, s71
	ds_write_b16_d16_hi v106, v0 offset:4480
	v_mul_f32_e32 v0, v25, v3
	v_bfe_u32 v2, v0, 16, 1
	v_add3_u32 v0, v0, v2, s71
	v_add_u32_e32 v2, 18, v6
	v_ashrrev_i32_e32 v3, 31, v2
	v_lshl_add_u64 v[2:3], v[2:3], 0, s[56:57]
	v_lshlrev_b64 v[2:3], 12, v[2:3]
	ds_write_b16_d16_hi v106, v0 offset:4544
	v_lshl_add_u64 v[2:3], s[10:11], 0, v[2:3]
	v_mul_f32_e32 v0, v74, v4
	v_lshl_add_u64 v[2:3], v[2:3], 0, s[6:7]
	v_bfe_u32 v7, v0, 16, 1
	v_lshl_add_u64 v[2:3], v[2:3], 0, v[140:141]
	v_add3_u32 v0, v0, v7, s71
	v_and_b32_e32 v108, -64, v2
	v_mov_b32_e32 v109, v3
	ds_write_b64 v107, v[108:109] offset:144
	ds_write_b16_d16_hi v106, v0 offset:4608
	v_mul_f32_e32 v0, v58, v4
	v_bfe_u32 v7, v0, 16, 1
	v_add3_u32 v0, v0, v7, s71
	ds_write_b16_d16_hi v106, v0 offset:4672
	v_mul_f32_e32 v0, v42, v4
	v_bfe_u32 v7, v0, 16, 1
	v_add3_u32 v0, v0, v7, s71
	ds_write_b16_d16_hi v106, v0 offset:4736
	v_mul_f32_e32 v0, v26, v4
	v_bfe_u32 v4, v0, 16, 1
	v_add3_u32 v0, v0, v4, s71
	ds_write_b16_d16_hi v106, v0 offset:4800
	v_add_u32_e32 v2, 19, v6
	v_ashrrev_i32_e32 v3, 31, v2
	v_lshl_add_u64 v[2:3], v[2:3], 0, s[56:57]
	v_lshlrev_b64 v[2:3], 12, v[2:3]
	v_lshl_add_u64 v[2:3], s[10:11], 0, v[2:3]
	v_mul_f32_e32 v0, v75, v5
	v_lshl_add_u64 v[2:3], v[2:3], 0, s[6:7]
	v_bfe_u32 v4, v0, 16, 1
	v_lshl_add_u64 v[2:3], v[2:3], 0, v[140:141]
	v_add3_u32 v0, v0, v4, s71
	v_and_b32_e32 v108, -64, v2
	v_mov_b32_e32 v109, v3
	ds_write_b64 v107, v[108:109] offset:152
	ds_write_b16_d16_hi v106, v0 offset:4864
	v_mul_f32_e32 v0, v59, v5
	v_bfe_u32 v4, v0, 16, 1
	v_add3_u32 v0, v0, v4, s71
	ds_write_b16_d16_hi v106, v0 offset:4928
	v_mul_f32_e32 v0, v43, v5
	v_bfe_u32 v4, v0, 16, 1
	v_add3_u32 v0, v0, v4, s71
	ds_write_b16_d16_hi v106, v0 offset:4992
	v_mul_f32_e32 v0, v27, v5
	v_bfe_u32 v4, v0, 16, 1
	v_add3_u32 v0, v0, v4, s71
	ds_write_b16_d16_hi v106, v0 offset:5056
	ds_read_b128 v[2:5], v158 offset:96
	v_add_u32_e32 v8, 24, v6
	v_ashrrev_i32_e32 v9, 31, v8
	v_lshl_add_u64 v[8:9], v[8:9], 0, s[56:57]
	v_lshlrev_b64 v[8:9], 12, v[8:9]
	v_lshl_add_u64 v[8:9], s[10:11], 0, v[8:9]
	s_waitcnt lgkmcnt(0)
	v_mul_f32_e32 v0, v76, v2
	v_lshl_add_u64 v[8:9], v[8:9], 0, s[6:7]
	v_bfe_u32 v7, v0, 16, 1
	v_lshl_add_u64 v[8:9], v[8:9], 0, v[140:141]
	v_add3_u32 v0, v0, v7, s71
	v_and_b32_e32 v108, -64, v8
	v_mov_b32_e32 v109, v9
	ds_write_b64 v107, v[108:109] offset:192
	ds_write_b16_d16_hi v106, v0 offset:6144
	v_mul_f32_e32 v0, v60, v2
	v_bfe_u32 v7, v0, 16, 1
	v_add3_u32 v0, v0, v7, s71
	ds_write_b16_d16_hi v106, v0 offset:6208
	v_mul_f32_e32 v0, v44, v2
	v_bfe_u32 v7, v0, 16, 1
	v_add3_u32 v0, v0, v7, s71
	ds_write_b16_d16_hi v106, v0 offset:6272
	v_mul_f32_e32 v0, v28, v2
	v_bfe_u32 v2, v0, 16, 1
	v_add3_u32 v0, v0, v2, s71
	ds_write_b16_d16_hi v106, v0 offset:6336
	v_add_u32_e32 v8, 25, v6
	v_ashrrev_i32_e32 v9, 31, v8
	v_lshl_add_u64 v[8:9], v[8:9], 0, s[56:57]
	v_lshlrev_b64 v[8:9], 12, v[8:9]
	v_lshl_add_u64 v[8:9], s[10:11], 0, v[8:9]
	v_mul_f32_e32 v0, v77, v3
	v_lshl_add_u64 v[8:9], v[8:9], 0, s[6:7]
	v_bfe_u32 v2, v0, 16, 1
	v_lshl_add_u64 v[8:9], v[8:9], 0, v[140:141]
	v_add3_u32 v0, v0, v2, s71
	v_and_b32_e32 v108, -64, v8
	v_mov_b32_e32 v109, v9
	ds_write_b64 v107, v[108:109] offset:200
	ds_write_b16_d16_hi v106, v0 offset:6400
	v_mul_f32_e32 v0, v61, v3
	v_bfe_u32 v2, v0, 16, 1
	v_add3_u32 v0, v0, v2, s71
	ds_write_b16_d16_hi v106, v0 offset:6464
	v_mul_f32_e32 v0, v45, v3
	v_bfe_u32 v2, v0, 16, 1
	v_add3_u32 v0, v0, v2, s71
	ds_write_b16_d16_hi v106, v0 offset:6528
	v_mul_f32_e32 v0, v29, v3
	v_bfe_u32 v2, v0, 16, 1
	v_add3_u32 v0, v0, v2, s71
	v_add_u32_e32 v2, 26, v6
	v_ashrrev_i32_e32 v3, 31, v2
	v_lshl_add_u64 v[2:3], v[2:3], 0, s[56:57]
	v_lshlrev_b64 v[2:3], 12, v[2:3]
	ds_write_b16_d16_hi v106, v0 offset:6592
	v_lshl_add_u64 v[2:3], s[10:11], 0, v[2:3]
	v_mul_f32_e32 v0, v78, v4
	v_lshl_add_u64 v[2:3], v[2:3], 0, s[6:7]
	v_bfe_u32 v7, v0, 16, 1
	v_lshl_add_u64 v[2:3], v[2:3], 0, v[140:141]
	v_add3_u32 v0, v0, v7, s71
	v_and_b32_e32 v108, -64, v2
	v_mov_b32_e32 v109, v3
	ds_write_b64 v107, v[108:109] offset:208
	ds_write_b16_d16_hi v106, v0 offset:6656
	v_mul_f32_e32 v0, v62, v4
	v_bfe_u32 v7, v0, 16, 1
	v_add3_u32 v0, v0, v7, s71
	ds_write_b16_d16_hi v106, v0 offset:6720
	v_mul_f32_e32 v0, v46, v4
	v_bfe_u32 v7, v0, 16, 1
	v_add3_u32 v0, v0, v7, s71
	ds_write_b16_d16_hi v106, v0 offset:6784
	v_mul_f32_e32 v0, v30, v4
	v_bfe_u32 v4, v0, 16, 1
	v_add3_u32 v0, v0, v4, s71
	ds_write_b16_d16_hi v106, v0 offset:6848
	v_add_u32_e32 v2, 27, v6
	v_ashrrev_i32_e32 v3, 31, v2
	v_lshl_add_u64 v[2:3], v[2:3], 0, s[56:57]
	v_lshlrev_b64 v[2:3], 12, v[2:3]
	v_lshl_add_u64 v[2:3], s[10:11], 0, v[2:3]
	v_mul_f32_e32 v0, v79, v5
	v_lshl_add_u64 v[2:3], v[2:3], 0, s[6:7]
	v_bfe_u32 v4, v0, 16, 1
	v_lshl_add_u64 v[2:3], v[2:3], 0, v[140:141]
	v_add3_u32 v0, v0, v4, s71
	v_and_b32_e32 v108, -64, v2
	v_mov_b32_e32 v109, v3
	ds_write_b64 v107, v[108:109] offset:216
	ds_write_b16_d16_hi v106, v0 offset:6912
	v_mul_f32_e32 v0, v63, v5
	v_bfe_u32 v4, v0, 16, 1
	v_add3_u32 v0, v0, v4, s71
	ds_write_b16_d16_hi v106, v0 offset:6976
	v_mul_f32_e32 v0, v47, v5
	v_bfe_u32 v4, v0, 16, 1
	v_add3_u32 v0, v0, v4, s71
	ds_write_b16_d16_hi v106, v0 offset:7040
	v_mul_f32_e32 v0, v31, v5
	v_bfe_u32 v4, v0, 16, 1
	s_add_i32 s24, s24, s21
	v_add3_u32 v0, v0, v4, s71
	s_cmpk_lt_i32 s24, 0x80
	ds_write_b16_d16_hi v106, v0 offset:7104
	v_lshrrev_b32_e32 v104, 4, v100
	v_and_b32_e32 v105, 15, v100
	v_lshlrev_b32_e32 v110, 8, v104
	v_lshl_add_u32 v110, v105, 4, v110
	v_add_u32_e32 v110, v102, v110
	v_lshl_add_u32 v111, v104, 3, v103
	v_lshlrev_b32_e32 v108, 4, v105
	v_mov_b32_e32 v109, 0
	ds_read_b128 v[2:5], v110
	ds_read_b128 v[6:9], v110 offset:1024
	ds_read_b128 v[10:13], v110 offset:2048
	ds_read_b128 v[14:17], v110 offset:3072
	ds_read_b128 v[18:21], v110 offset:4096
	ds_read_b128 v[22:25], v110 offset:5120
	ds_read_b128 v[26:29], v110 offset:6144
	ds_read_b128 v[30:33], v110 offset:7168
	ds_read_b64 v[34:35], v111
	ds_read_b64 v[36:37], v111 offset:32
	ds_read_b64 v[38:39], v111 offset:64
	ds_read_b64 v[40:41], v111 offset:96
	ds_read_b64 v[42:43], v111 offset:128
	ds_read_b64 v[44:45], v111 offset:160
	ds_read_b64 v[46:47], v111 offset:192
	ds_read_b64 v[48:49], v111 offset:224
	s_waitcnt lgkmcnt(0)
	v_lshl_add_u64 v[34:35], v[34:35], 0, v[108:109]
	global_store_dwordx4 v[34:35], v[2:5], off offset:2048
	v_lshl_add_u64 v[36:37], v[36:37], 0, v[108:109]
	global_store_dwordx4 v[36:37], v[6:9], off offset:2048
	v_lshl_add_u64 v[38:39], v[38:39], 0, v[108:109]
	global_store_dwordx4 v[38:39], v[10:13], off offset:2048
	v_lshl_add_u64 v[40:41], v[40:41], 0, v[108:109]
	global_store_dwordx4 v[40:41], v[14:17], off offset:2048
	v_lshl_add_u64 v[42:43], v[42:43], 0, v[108:109]
	global_store_dwordx4 v[42:43], v[18:21], off offset:2048
	v_lshl_add_u64 v[44:45], v[44:45], 0, v[108:109]
	global_store_dwordx4 v[44:45], v[22:25], off offset:2048
	v_lshl_add_u64 v[46:47], v[46:47], 0, v[108:109]
	global_store_dwordx4 v[46:47], v[26:29], off offset:2048
	v_lshl_add_u64 v[48:49], v[48:49], 0, v[108:109]
	global_store_dwordx4 v[48:49], v[30:33], off offset:2048
	s_cbranch_scc0 .LBB0_328
